# SSD: conv rows of wave 4 spread over waves 4-7, logical wave roles permuted to balance CB/Y tiles per SIMD, CB MFMA chain with 4-deep LDS fragment prefetch
# speedup vs baseline: 1.0064x; 1.0064x over previous
; #define LAS __attribute__((address_space(3)))
; __device__ __forceinline__ int otid() { int t = threadIdx.x; asm volatile("" : "+v"(t)); return t; }
; __device__ __forceinline__ void ssd_item(const Params& p, LAS unsigned char* lds, int bl, int head, int dry) {
;     const int tid = otid(), w = tid >> 6, lane = tid & 63; const int T = p.T;
;     bf16_t* proj = (bf16_t*)(p.ws + ws_proj(T)); const float* dtraw = (const float*)(p.ws + ws_dt(T));
;     LAS bf16_t* CM = (LAS bf16_t*)(lds + L_CM); LAS bf16_t* BMm = (LAS bf16_t*)(lds + L_BM); LAS bf16_t* BT = (LAS bf16_t*)(lds + L_BT);
;     LAS bf16_t* XT = (LAS bf16_t*)(lds + L_XT); LAS bf16_t* SB = (LAS bf16_t*)(lds + L_SB);
;     LAS float* fs = (LAS float*)(lds + L_FA);
;     const float Ah = -__expf(p.a_log[head]), Dh = p.d_skip[head], dtb = p.dt_bias[head];
;     const int g = head >> 2; const size_t rowbase = (size_t)bl * SEQ;
;     const int pt = w >> 2, nt = w & 3;
;     const int rsub = 4 * (lane >> 5), cl = lane & 31;
;     const bool cact = tid < 320; const int cq = tid % 80, rg = (tid / 80) & 3, rgc = tid < 320 ? tid / 80 : 3;
;     int kind, n4, col, ch;
;     if (cq < 16) { kind = 0; n4 = 4 * cq; col = COL_XBC + head * 64 + n4; ch = head * 64 + n4; }
;     else if (cq < 48) { kind = 1; n4 = 4 * (cq - 16); col = COL_XBC + 2048 + g * 128 + n4; ch = 2048 + g * 128 + n4; }
;     else { kind = 2; n4 = 4 * (cq - 48); col = COL_XBC + 3072 + g * 128 + n4; ch = 3072 + g * 128 + n4; }
.LBB0_204:
	s_lshl_b32 s0, s4, 2
	s_and_b32 s6, s0, 28
	s_bfe_u32 s0, s4, 0x20003
	s_or_b32 s12, s6, s0
	s_lshl_b32 s2, s12, 2
	v_readlane_b32 s16, v245, 29
	v_mov_b32_e32 v160, v220
	v_readfirstlane_b32 s98, v220
	s_nop 3
	s_lshr_b32 s98, s98, 6
	s_sub_i32 s99, s98, 4
	s_max_i32 s99, s99, 0
	s_lshl_b32 s99, s99, 3
	s_mul_i32 s101, s99, 0x110
	v_and_b32_e32 v246, 63, v220
	v_add_u32_e32 v246, 0x100, v246
	v_cmp_gt_u32_e32 vcc, 0x140, v220
	s_nop 1
	v_cndmask_b32_e32 v246, v246, v220, vcc
	s_cmp_ge_u32 s98, 4
	s_cselect_b32 s100, 0xc0, 0
	v_xor_b32_e32 v160, s100, v160
	v_mov_b32_e32 v0, s2
	v_readlane_b32 s28, v245, 41
	v_readlane_b32 s29, v245, 42
	v_readlane_b32 s26, v245, 39
	v_readlane_b32 s27, v245, 40
	v_readlane_b32 s30, v245, 43
	v_readlane_b32 s31, v245, 44
	s_nop 0
	global_load_dword v5, v0, s[28:29]
	s_nop 2
	global_load_dword v161, v0, s[30:31]
	global_load_dword v162, v0, s[26:27]
	s_mov_b32 s0, 0x66666667
	v_mul_hi_i32 v0, v246, s0
	s_waitcnt lgkmcnt(0)
	v_lshrrev_b32_e32 v1, 31, v0
	v_ashrrev_i32_e32 v0, 5, v0
	v_add_u32_e32 v3, v0, v1
	s_movk_i32 s0, 0x50
	v_mul_lo_u32 v0, v3, s0
	v_readlane_b32 s24, v245, 37
	v_readlane_b32 s25, v245, 38
	v_sub_u32_e32 v1, v246, v0
	v_cmp_gt_i32_e64 s[24:25], 16, v1
	v_cmp_lt_i32_e64 s[38:39], 15, v1
	v_lshlrev_b32_e32 v2, 2, v1
	v_writelane_b32 v243, s4, 42
	v_readlane_b32 s17, v245, 30
	v_readlane_b32 s18, v245, 31
	v_readlane_b32 s19, v245, 32
	v_readlane_b32 s20, v245, 33
	v_readlane_b32 s21, v245, 34
	v_readlane_b32 s22, v245, 35
	v_readlane_b32 s23, v245, 36
	s_and_saveexec_b64 s[0:1], s[38:39]
	v_readlane_b32 s14, v243, 26
	s_xor_b64 s[0:1], exec, s[0:1]
	v_readlane_b32 s15, v243, 27
	s_cbranch_execz .LBB0_210
	v_cmp_lt_u32_e32 vcc, 47, v1
	v_lshlrev_b32_e32 v1, 2, v1
	s_lshl_b32 s8, s6, 5
	s_and_saveexec_b64 s[4:5], vcc
	s_xor_b64 s[4:5], exec, s[4:5]
	v_add_u32_e32 v2, 0xffffff40, v1
	v_add_u32_e32 v0, s8, v2
	v_add_u32_e32 v6, 0x1400, v0
	v_add_u32_e32 v0, 0xc00, v0
	s_or_saveexec_b64 s[6:7], s[4:5]
	v_mov_b32_e32 v4, 0
	s_mov_b64 s[4:5], -1
	s_xor_b64 exec, exec, s[6:7]
	s_cbranch_execz .LBB0_209
	v_subrev_u32_e32 v2, 64, v1
	v_add_u32_e32 v0, s8, v2
	v_readlane_b32 s4, v243, 1
	v_add_u32_e32 v6, 0x1000, v0
	v_add_u32_e32 v0, 0x800, v0
	v_mov_b32_e32 v4, s4
	s_xor_b64 s[4:5], exec, -1

; #define LAS __attribute__((address_space(3)))
; __device__ __forceinline__ f32x16 mma32_k8(const LAS bf16_t* A, const LAS bf16_t* B, f32x16 acc, int lane) {
;     const LAS bf16_t* ap = A + (lane & 31) * SLD + (lane >> 5) * 8; const LAS bf16_t* bp = B + (lane & 31) * SLD + (lane >> 5) * 8;
; #pragma unroll
;     for (int h = 0; h < 2; ++h) {
;         bf16x8 a[4], b[4];
; #pragma unroll
;         for (int ks = 0; ks < 4; ++ks) { a[ks] = *(const LAS bf16x8*)(ap + (h * 4 + ks) * 16); b[ks] = *(const LAS bf16x8*)(bp + (h * 4 + ks) * 16); }
; #pragma unroll
;         for (int ks = 0; ks < 4; ++ks) acc = __builtin_amdgcn_mfma_f32_32x32x16_bf16(a[ks], b[ks], acc, 0, 0, 0);
;     }
;     return acc;
; }
.LBB0_242:
	s_or_b64 exec, exec, s[56:57]
	v_max_i32_e32 v17, 0, v16
	v_mad_u64_u32 v[18:19], s[56:57], v17, s33, v[68:69]
	v_max_i32_e32 v17, -1, v16
	v_add_u32_e32 v17, 1, v17
	v_mad_u64_u32 v[20:21], s[56:57], v17, s33, v[68:69]
	v_max_i32_e32 v17, -2, v16
	v_add_u32_e32 v17, 2, v17
	v_add_u32_e32 v16, 3, v16
	v_mad_u64_u32 v[22:23], s[56:57], v17, s33, v[68:69]
	v_mad_i64_i32 v[16:17], s[56:57], v16, s33, v[68:69]
	global_load_dwordx2 v[150:151], v[18:19], off
	global_load_dwordx2 v[152:153], v[20:21], off
	global_load_dwordx2 v[154:155], v[22:23], off
	global_load_dwordx2 v[148:149], v[16:17], off
	v_lshl_add_u64 v[16:17], v[16:17], 0, v[168:169]
	v_lshl_add_u64 v[18:19], v[16:17], 0, v[168:169]
	v_lshl_add_u64 v[20:21], v[18:19], 0, v[168:169]
	global_load_dwordx2 v[146:147], v[16:17], off
	global_load_dwordx2 v[144:145], v[18:19], off
	global_load_dwordx2 v[142:143], v[20:21], off
	v_lshl_add_u64 v[16:17], v[20:21], 0, v[168:169]
	global_load_dwordx2 v[140:141], v[16:17], off
	v_lshl_add_u64 v[16:17], v[16:17], 0, v[168:169]
	global_load_dwordx2 v[138:139], v[16:17], off
	v_lshl_add_u64 v[16:17], v[16:17], 0, v[168:169]
	global_load_dwordx2 v[136:137], v[16:17], off
	v_lshl_add_u64 v[16:17], v[16:17], 0, v[168:169]
	global_load_dwordx2 v[134:135], v[16:17], off
	v_lshl_add_u64 v[16:17], v[16:17], 0, v[246:247]
	global_load_dwordx2 v[132:133], v[16:17], off
	v_lshl_add_u64 v[16:17], v[16:17], 0, v[246:247]
	global_load_dwordx2 v[130:131], v[16:17], off
	v_lshl_add_u64 v[16:17], v[16:17], 0, v[246:247]
	global_load_dwordx2 v[128:129], v[16:17], off
	v_lshl_add_u64 v[16:17], v[16:17], 0, v[246:247]
	global_load_dwordx2 v[126:127], v[16:17], off
	v_lshl_add_u64 v[16:17], v[16:17], 0, v[246:247]
	global_load_dwordx2 v[124:125], v[16:17], off
	v_lshl_add_u64 v[16:17], v[16:17], 0, v[246:247]
	global_load_dwordx2 v[122:123], v[16:17], off
	v_lshl_add_u64 v[16:17], v[16:17], 0, v[246:247]
	global_load_dwordx2 v[120:121], v[16:17], off
	v_lshl_add_u64 v[16:17], v[16:17], 0, v[246:247]
	global_load_dwordx2 v[118:119], v[16:17], off
	v_lshl_add_u64 v[16:17], v[16:17], 0, v[246:247]
	global_load_dwordx2 v[116:117], v[16:17], off
	v_lshl_add_u64 v[16:17], v[16:17], 0, v[246:247]
	global_load_dwordx2 v[114:115], v[16:17], off
	v_lshl_add_u64 v[16:17], v[16:17], 0, v[246:247]
	global_load_dwordx2 v[112:113], v[16:17], off
	v_lshl_add_u64 v[16:17], v[16:17], 0, v[246:247]
	global_load_dwordx2 v[110:111], v[16:17], off
	v_lshl_add_u64 v[16:17], v[16:17], 0, v[246:247]
	global_load_dwordx2 v[108:109], v[16:17], off
	v_lshl_add_u64 v[16:17], v[16:17], 0, v[246:247]
	global_load_dwordx2 v[106:107], v[16:17], off
	v_lshl_add_u64 v[16:17], v[16:17], 0, v[246:247]
	global_load_dwordx2 v[102:103], v[16:17], off
	v_lshl_add_u64 v[16:17], v[16:17], 0, v[246:247]
	global_load_dwordx2 v[100:101], v[16:17], off
	v_lshl_add_u64 v[16:17], v[16:17], 0, v[246:247]
	global_load_dwordx2 v[94:95], v[16:17], off
	v_lshl_add_u64 v[16:17], v[16:17], 0, v[246:247]
	global_load_dwordx2 v[92:93], v[16:17], off
	v_lshl_add_u64 v[16:17], v[16:17], 0, v[246:247]
	global_load_dwordx2 v[88:89], v[16:17], off
	v_lshl_add_u64 v[16:17], v[16:17], 0, v[246:247]
	global_load_dwordx2 v[86:87], v[16:17], off
	v_lshl_add_u64 v[16:17], v[16:17], 0, v[246:247]
	global_load_dwordx2 v[84:85], v[16:17], off
	v_lshl_add_u64 v[16:17], v[16:17], 0, v[246:247]
	global_load_dwordx2 v[82:83], v[16:17], off
	v_lshl_add_u64 v[16:17], v[16:17], 0, v[246:247]
	global_load_dwordx2 v[80:81], v[16:17], off
	v_lshl_add_u64 v[16:17], v[16:17], 0, v[246:247]
	global_load_dwordx2 v[78:79], v[16:17], off
	v_mov_b32_e32 v16, 0
	v_mov_b32_e32 v32, 0
	v_mov_b32_e32 v33, 0
	v_mov_b32_e32 v34, 0
	v_mov_b32_e32 v35, 0
	v_mov_b32_e32 v36, 0
	v_mov_b32_e32 v37, 0
	v_mov_b32_e32 v38, 0
	v_mov_b32_e32 v39, 0
	v_mov_b32_e32 v40, 0
	v_mov_b32_e32 v41, 0
	v_mov_b32_e32 v42, 0
	v_mov_b32_e32 v43, 0
	v_mov_b32_e32 v44, 0
	v_mov_b32_e32 v45, 0
	v_mov_b32_e32 v46, 0
	v_mov_b32_e32 v47, 0
	s_waitcnt lgkmcnt(0)
	s_barrier
	s_and_saveexec_b64 s[56:57], s[46:47]
	s_cbranch_execz .LBB0_244
	ds_read_b128 v[16:19], v188
	ds_read_b128 v[194:197], v171 offset:34816
	ds_read_b128 v[20:23], v188 offset:32
	ds_read_b128 v[198:201], v171 offset:34848
	ds_read_b128 v[24:27], v188 offset:64
	ds_read_b128 v[202:205], v171 offset:34880
	ds_read_b128 v[28:31], v188 offset:96
	ds_read_b128 v[206:209], v171 offset:34912
	s_waitcnt lgkmcnt(6)
	v_mfma_f32_32x32x16_bf16 v[32:47], v[16:19], v[194:197], 0
	ds_read_b128 v[16:19], v188 offset:128
	ds_read_b128 v[194:197], v171 offset:34944
	s_waitcnt lgkmcnt(6)
	v_mfma_f32_32x32x16_bf16 v[32:47], v[20:23], v[198:201], v[32:47]
	ds_read_b128 v[20:23], v188 offset:160
	ds_read_b128 v[198:201], v171 offset:34976
	s_waitcnt lgkmcnt(6)
	v_mfma_f32_32x32x16_bf16 v[32:47], v[24:27], v[202:205], v[32:47]
	ds_read_b128 v[24:27], v188 offset:192
	ds_read_b128 v[202:205], v171 offset:35008
	s_waitcnt lgkmcnt(6)
	v_mfma_f32_32x32x16_bf16 v[32:47], v[28:31], v[206:209], v[32:47]
	ds_read_b128 v[28:31], v188 offset:224
	ds_read_b128 v[206:209], v171 offset:35040
	s_waitcnt lgkmcnt(6)
	v_mfma_f32_32x32x16_bf16 v[32:47], v[16:19], v[194:197], v[32:47]
	s_waitcnt lgkmcnt(4)
	v_mfma_f32_32x32x16_bf16 v[32:47], v[20:23], v[198:201], v[32:47]
	s_waitcnt lgkmcnt(2)
	v_mfma_f32_32x32x16_bf16 v[32:47], v[24:27], v[202:205], v[32:47]
	s_waitcnt lgkmcnt(0)
	v_mfma_f32_32x32x16_bf16 v[32:47], v[28:31], v[206:209], v[32:47]
; #define LAS __attribute__((address_space(3)))
; __device__ __forceinline__ f32x16 mma32_k8(const LAS bf16_t* A, const LAS bf16_t* B, f32x16 acc, int lane) {
;     const LAS bf16_t* ap = A + (lane & 31) * SLD + (lane >> 5) * 8; const LAS bf16_t* bp = B + (lane & 31) * SLD + (lane >> 5) * 8;
; #pragma unroll
;     for (int h = 0; h < 2; ++h) {
;         bf16x8 a[4], b[4];
; #pragma unroll
;         for (int ks = 0; ks < 4; ++ks) { a[ks] = *(const LAS bf16x8*)(ap + (h * 4 + ks) * 16); b[ks] = *(const LAS bf16x8*)(bp + (h * 4 + ks) * 16); }
; #pragma unroll
;         for (int ks = 0; ks < 4; ++ks) acc = __builtin_amdgcn_mfma_f32_32x32x16_bf16(a[ks], b[ks], acc, 0, 0, 0);
;     }
;     return acc;
; }
; __device__ __forceinline__ void ssd_item(const Params& p, LAS unsigned char* lds, int bl, int head, int dry) {
;     ...
;         for (int q = 0; q < 2; ++q) { const int id = w + 8 * q; ti[q] = id >> 2; tj[q] = id & 3;
; #pragma unroll
;             for (int i = 0; i < 16; ++i) cb[q][i] = 0.f;
;             if (tj[q] <= ti[q]) cb[q] = mma32_k8(CM + ti[q] * 32 * SLD, BMm + tj[q] * 32 * SLD, cb[q], lane); }
.LBB0_244:
	s_or_b64 exec, exec, s[56:57]
	v_mov_b32_e32 v16, 0
	v_mov_b32_e32 v17, 0
	v_mov_b32_e32 v18, 0
	v_mov_b32_e32 v19, 0
	v_mov_b32_e32 v20, 0
	v_mov_b32_e32 v21, 0
	v_mov_b32_e32 v22, 0
	v_mov_b32_e32 v23, 0
	v_mov_b32_e32 v24, 0
	v_mov_b32_e32 v25, 0
	v_mov_b32_e32 v26, 0
	v_mov_b32_e32 v27, 0
	v_mov_b32_e32 v28, 0
	v_mov_b32_e32 v29, 0
	v_mov_b32_e32 v30, 0
	v_mov_b32_e32 v31, 0
	s_and_saveexec_b64 s[56:57], s[48:49]
	s_cbranch_execz .LBB0_246
	ds_read_b128 v[194:197], v189
	ds_read_b128 v[206:209], v171 offset:34816
	ds_read_b128 v[198:201], v189 offset:32
	ds_read_b128 v[210:213], v171 offset:34848
	ds_read_b128 v[202:205], v189 offset:64
	ds_read_b128 v[214:217], v171 offset:34880
	s_waitcnt lgkmcnt(4)
	v_mfma_f32_32x32x16_bf16 v[16:31], v[194:197], v[206:209], 0
	ds_read_b128 v[194:197], v189 offset:96
	ds_read_b128 v[206:209], v171 offset:34912
	s_waitcnt lgkmcnt(4)
	v_mfma_f32_32x32x16_bf16 v[16:31], v[198:201], v[210:213], v[16:31]
	ds_read_b128 v[198:201], v189 offset:128
	ds_read_b128 v[210:213], v171 offset:34944
	s_waitcnt lgkmcnt(4)
	v_mfma_f32_32x32x16_bf16 v[16:31], v[202:205], v[214:217], v[16:31]
	ds_read_b128 v[202:205], v189 offset:160
	ds_read_b128 v[214:217], v171 offset:34976
	s_waitcnt lgkmcnt(4)
	v_mfma_f32_32x32x16_bf16 v[16:31], v[194:197], v[206:209], v[16:31]
	ds_read_b128 v[194:197], v189 offset:192
	ds_read_b128 v[206:209], v171 offset:35008
	s_waitcnt lgkmcnt(4)
	v_mfma_f32_32x32x16_bf16 v[16:31], v[198:201], v[210:213], v[16:31]
	ds_read_b128 v[198:201], v189 offset:224
	ds_read_b128 v[210:213], v171 offset:35040
	s_waitcnt lgkmcnt(4)
	v_mfma_f32_32x32x16_bf16 v[16:31], v[202:205], v[214:217], v[16:31]
	s_waitcnt lgkmcnt(2)
	v_mfma_f32_32x32x16_bf16 v[16:31], v[194:197], v[206:209], v[16:31]
	s_waitcnt lgkmcnt(0)
	v_mfma_f32_32x32x16_bf16 v[16:31], v[198:201], v[210:213], v[16:31]
